# stagger P1 start of workgroup groups by 0-4.5us (desynchronises epilogue store bursts) on top of fast epilogue
# speedup vs baseline: 1.0243x; 1.0132x over previous
; #define PG8_STAGE(bufoff, gbase, voff) do { _Pragma("unroll") for (int _i = 0; _i < 2; ++_i) \
;         __builtin_amdgcn_global_load_lds((const unsigned*)((const char*)(gbase) + (voff)[_i]), (PG8_LAS unsigned*)(lds + (bufoff) + ldsw + _i * 8192), 16, 0, 0); } while (0)
; #define PG8_WAIT_V(n) asm volatile("s_waitcnt vmcnt(" #n ")" ::: "memory")
; #define PG8_BAR __builtin_amdgcn_s_barrier()
;     DI static int pn_a(int s) { return (s < 3) ? s : (s == 3) ? 9 : (s == 4) ? 10 : 13; }
;     DI static int pn_b(int s) { return (s < 6) ? 3 + s : 5 + s; }
;     DI bool next(int i, pg8::Unit& u) const { if (i > 0 || !valid) return false; u.pm = pm; u.pn = pn; return true; }
; template <class Epi, class Sched, bool ALIGN_EPI = false, bool SP2 = false, bool PRE = false>
; __device__ __forceinline__ void gemm_phase(PG8_LAS unsigned char* lds, const Gemm g, const Sched& S, const Epi& E, const f32x4 (*pre)[2][4][2] = nullptr) {
;     ...
;     const char* cA = (const char*)g.A + (size_t)cur.pm * tstep; const char* cB = (const char*)g.Bt + (size_t)cur.pn * tstep;
;     S.a_ready(cur);
;     if constexpr (SP2) {
;         PG8_STAGE(PG8_SB(0, 0), cB, voffB); PG8_STAGE(PG8_SB(0, 1), cB + hstep, voffB); PG8_STAGE(PG8_SA(0, 0), cA, voffA); PG8_STAGE(PG8_SA(0, 1), cA + hstep, voffA);
;         if (wr == 1) PG8_BAR;
;         PG8_WAIT_V(2); PG8_BAR;
;         PG8_STAGE(PG8_SB(1, 0), cB + kstep, voffB); PG8_STAGE(PG8_SA(1, 0), cA + kstep, voffA); PG8_STAGE(PG8_SB(1, 1), cB + hstep + kstep, voffB);
;     DI bool next(int i, pg8::Unit& u) const {
;         const int L = i * G + c; if (L >= NU_P1) return false;
;         u.fl = (L < NA && L + G >= NA) ? 1 : 0;
;         const int xcd = L & 7;
;         if (L < NA) { const int wg = xcd * (NA / 8) + (L >> 3);
;             if (wg >= NA - 4) { const int e = wg - (NA - 4); u.pm = NPM + (e >> 1); u.pn = NPN_IN + (e & 1); return true; }
;             if (wg >= 384) { const int w = wg - 384, s = w >> 1; u.pm = 64 + (w & 1); u.pn = (s < 6) ? pn_a(s) : pn_b(s - 6); return true; }
;             const int gid = wg / 48, fm = gid * 8, within = wg % 48;
;             u.pm = fm + (within & 7); u.pn = pn_a(within >> 3); return true; }
;         const int wg = xcd * 64 + ((L - NA) >> 3), gid = wg >> 6, fm = gid * 8, within = wg & 63;
;         u.pm = fm + (within & 7); u.pn = pn_b(within >> 3); return true;
.LBB0_162:
	s_waitcnt lgkmcnt(0)
	v_writelane_b32 v247, s36, 25
	s_mov_b64 s[0:1], s[52:53]
	s_mov_b32 s2, s54
	v_writelane_b32 v247, s37, 26
	v_writelane_b32 v247, s38, 27
	v_writelane_b32 v247, s39, 28
	v_writelane_b32 v247, s40, 29
	v_writelane_b32 v247, s41, 30
	v_writelane_b32 v247, s42, 31
	v_writelane_b32 v247, s43, 32
	v_writelane_b32 v247, s44, 33
	v_writelane_b32 v247, s45, 34
	v_writelane_b32 v247, s46, 35
	v_writelane_b32 v247, s47, 36
	v_writelane_b32 v247, s48, 37
	v_writelane_b32 v247, s49, 38
	v_writelane_b32 v247, s50, 39
	v_writelane_b32 v247, s51, 40
	v_writelane_b32 v247, s0, 41
	s_cmp_lt_i32 s52, 2
	s_cselect_b64 s[12:13], -1, 0
	v_writelane_b32 v247, s1, 42
	v_writelane_b32 v247, s2, 43
	v_writelane_b32 v247, s3, 44
	s_add_u32 s0, s82, 0x3400000
	s_addc_u32 s1, s83, 0
	s_add_u32 s76, s82, 0x5a00000
	s_addc_u32 s77, s83, 0
	s_add_u32 s60, s82, 0x7e00000
	s_addc_u32 s61, s83, 0
	s_add_u32 s64, s82, 0xaa00000
	s_addc_u32 s65, s83, 0
	s_add_u32 s36, s82, 0xe000000
	s_addc_u32 s37, s83, 0
	s_add_u32 s62, s82, 0x3e00000
	v_writelane_b32 v247, s0, 45
	s_addc_u32 s63, s83, 0
	s_add_u32 s78, s82, 0x4800000
	v_writelane_b32 v247, s1, 46
	s_addc_u32 s79, s83, 0
	v_writelane_b32 v247, s96, 47
	s_add_u32 s80, s82, 0x6c00000
	v_writelane_b32 v247, s97, 48
	s_addc_u32 s81, s83, 0
	v_writelane_b32 v247, s58, 49
	s_add_u32 s24, s82, 0x8800000
	s_addc_u32 s25, s83, 0
	v_writelane_b32 v247, s59, 50
	v_writelane_b32 v247, s60, 51
	s_add_u32 s66, s82, 0xab00000
	s_addc_u32 s67, s83, 0
	v_writelane_b32 v247, s61, 52
	s_and_b64 s[70:71], s[12:13], s[4:5]
	v_writelane_b32 v247, s65, 53
	s_andn2_b64 vcc, exec, s[70:71]
	v_writelane_b32 v247, s66, 54
	v_writelane_b32 v247, s67, 55
	s_cbranch_vccnz .LBB0_536
	s_lshr_b32 s40, s96, 3
	s_and_b32 s40, s40, 3
.Lstag:
	s_cmp_eq_u32 s40, 0
	s_cbranch_scc1 .Lstag_done
	s_sleep 48
	s_sub_u32 s40, s40, 1
	s_branch .Lstag
.Lstag_done:
	s_cmpk_gt_i32 s96, 0x39f
	s_cselect_b64 s[0:1], -1, 0
	s_add_u32 s16, s82, 0x13400
	s_addc_u32 s17, s83, 0
	v_readfirstlane_b32 s2, v0
	s_and_b64 vcc, exec, s[0:1]
	s_cbranch_vccnz .LBB0_478
	v_lshrrev_b32_e32 v3, 1, v0
	v_and_b32_e32 v13, 24, v3
	v_lshrrev_b32_e32 v3, 5, v0
	v_lshlrev_b32_e32 v1, 4, v0
	v_and_b32_e32 v2, 32, v0
	v_and_b32_e32 v3, 4, v3
	v_bfe_u32 v4, v0, 2, 2
	v_bfe_u32 v12, v0, 2, 4
	v_bitop3_b32 v10, v1, v2, 48 bitop3:0x6c
	v_and_b32_e32 v11, 64, v0
	v_or3_b32 v3, v3, v4, v13
	v_lshrrev_b32_e32 v4, 3, v0
	v_or_b32_e32 v14, 0x2000, v1
	v_or_b32_e32 v2, v10, v11
	v_and_or_b32 v5, v4, 48, v12
	v_and_or_b32 v4, v4, 32, v3
	v_lshrrev_b32_e32 v1, 7, v14
	s_movk_i32 s0, 0x70
	v_lshl_or_b32 v138, v4, 11, v2
	v_and_or_b32 v4, v1, s0, v12
	s_movk_i32 s0, 0x60
	v_and_or_b32 v1, v1, s0, v3
	s_and_b32 s0, s96, 7
	s_add_i32 s3, s96, 0xfffffe60
	s_lshl_b32 s1, s0, 6
	s_lshr_b32 s4, s3, 3
	s_add_i32 s1, s1, s4
	s_lshr_b32 s1, s1, 3
	s_and_b32 s1, s1, 0x7fffff8
	s_bfe_u32 s4, s3, 0x30003
	s_or_b32 s4, s1, s4
	s_lshr_b32 s1, s3, 6
	s_cmpk_gt_u32 s3, 0x17f
	s_cselect_b32 s3, 5, 3
	s_add_i32 s5, s3, s1
	s_mul_i32 s0, s0, 52
	s_ashr_i32 s1, s96, 3
	s_add_i32 s0, s0, s1
	s_mul_hi_i32 s3, s0, 0x2aaaaaab
	s_lshr_b32 s6, s3, 31
	s_ashr_i32 s3, s3, 3
	s_add_i32 s3, s3, s6
	s_lshl_b32 s6, s3, 3
	s_mul_i32 s3, s3, 48
	s_sub_i32 s3, s0, s3
	s_and_b32 s7, s3, 7
	s_or_b32 s6, s6, s7
	s_ashr_i32 s3, s3, 3
	v_writelane_b32 v247, s16, 56
	s_cmp_eq_u32 s3, 4
	s_cselect_b32 s7, 10, 13
	v_writelane_b32 v247, s17, 57
	s_cmp_lg_u32 s3, 3
	v_writelane_b32 v247, s70, 58
	s_cselect_b32 s7, s7, 9
	s_cmp_lt_i32 s3, 3
	v_writelane_b32 v247, s71, 59
	s_cselect_b32 s7, s3, s7
	s_add_i32 s8, s0, 0xfffffe80
	v_writelane_b32 v247, s12, 60
	s_lshr_b32 s3, s8, 1
	s_and_b32 s1, s1, 1
	v_writelane_b32 v247, s13, 61
	s_or_b32 s9, s1, 64
	s_add_i32 s12, s3, -6
	s_cmp_gt_u32 s12, 5
	s_cselect_b32 s13, 5, 3
	s_add_i32 s13, s13, s12
	s_cmp_eq_u32 s3, 4
	s_cselect_b32 s12, 10, 13
	s_cmp_lg_u32 s3, 3
	s_cselect_b32 s12, s12, 9
	s_cmp_lt_u32 s8, 6
	s_cselect_b32 s16, s3, s12
	s_add_i32 s3, s0, 0xfffffe64
	s_lshr_b32 s3, s3, 1
	s_add_i32 s17, s3, 0x42
	s_lshr_b32 s3, s2, 6
	s_or_b32 s18, s1, 14
	s_lshr_b32 s12, s2, 8
	s_lshl_b32 s30, s3, 10
	s_cmp_lt_u32 s8, 12
	s_cselect_b32 s1, s16, s13
	s_cmpk_gt_i32 s0, 0x17f
	s_cselect_b32 s7, s1, s7
	s_cselect_b32 s6, s9, s6
	s_cmpk_lt_i32 s0, 0x19c
	s_cselect_b64 s[0:1], -1, 0
	s_and_b64 s[0:1], s[0:1], exec
	s_cselect_b32 s7, s7, s18
	s_cselect_b32 s6, s6, s17
	s_cmpk_lt_i32 s96, 0x1a0
	s_cselect_b64 s[8:9], -1, 0
	s_and_b64 s[0:1], s[8:9], exec
	s_cselect_b32 s90, s7, s5
	s_cselect_b32 s0, s6, s4
	s_ashr_i32 s1, s0, 31
	s_ashr_i32 s91, s90, 31
	s_lshl_b64 s[4:5], s[0:1], 19
	s_lshl_b64 s[6:7], s[90:91], 19
	s_add_u32 s6, s10, s6
	s_addc_u32 s7, s11, s7
	s_add_i32 s31, s30, 0
	s_add_i32 m0, s31, 0x10000
	v_lshl_or_b32 v142, v1, 11, v2
	global_load_lds_dwordx4 v138, s[6:7]
	s_add_i32 m0, s31, 0x12000
	s_add_u32 s16, s6, 0x40000
	global_load_lds_dwordx4 v142, s[6:7]
	s_addc_u32 s17, s7, 0
	s_add_i32 m0, s31, 0x14000
	v_lshl_or_b32 v136, v5, 11, v2
	global_load_lds_dwordx4 v138, s[16:17]
	s_add_i32 m0, s31, 0x16000
	s_add_u32 s4, s14, s4
	s_addc_u32 s5, s15, s5
	s_add_i32 s40, s31, 0x2000
	global_load_lds_dwordx4 v142, s[16:17]
	s_mov_b32 m0, s31
	s_add_u32 s16, s4, 0x40000
	v_lshl_or_b32 v140, v4, 11, v2
	global_load_lds_dwordx4 v136, s[4:5]
	s_mov_b32 m0, s40
	s_addc_u32 s17, s5, 0
	s_add_i32 s41, s31, 0x4000
	global_load_lds_dwordx4 v140, s[4:5]
	s_mov_b32 m0, s41
	s_add_i32 s44, s31, 0x6000
	global_load_lds_dwordx4 v136, s[16:17]
	s_mov_b32 m0, s44
	s_mov_b32 s1, 0
	global_load_lds_dwordx4 v140, s[16:17]
	v_mov_b32_e32 v145, 0
	v_writelane_b32 v246, s0, 1
	s_cmp_eq_u32 s12, 1
	v_mov_b32_e32 v139, v145
	v_mov_b32_e32 v143, v145
	v_mov_b32_e32 v137, v145
	v_mov_b32_e32 v141, v145
	v_writelane_b32 v246, s1, 2
	s_cselect_b64 s[16:17], -1, 0
	v_writelane_b32 v247, s64, 62
	s_mov_b64 s[58:59], s[62:63]
	v_lshl_add_u64 v[8:9], s[6:7], 0, v[138:139]
	v_lshl_add_u64 v[6:7], s[6:7], 0, v[142:143]
	v_lshl_add_u64 v[2:3], s[4:5], 0, v[136:137]
	v_writelane_b32 v246, s16, 3
	s_cmp_lg_u32 s12, 1
	v_lshl_add_u64 v[4:5], s[4:5], 0, v[140:141]
	v_writelane_b32 v247, s84, 63
	v_writelane_b32 v246, s17, 4
	s_cbranch_scc1 .LBB0_166
	s_barrier
